# stack2: + P0 weight-transpose loads fully unrolled (32 loads in flight per item) and gain-vector loads hoisted ahead of tile loads
# speedup vs baseline: 1.0063x; 1.0039x over previous
; #define GAS __attribute__((address_space(1)))
; #define LAS __attribute__((address_space(3)))
; #define LDS_WAIT() asm volatile("s_waitcnt lgkmcnt(0)" ::: "memory")
; __device__ __forceinline__ unsigned pk2(float lo, float hi) { return f2bf(lo) | (f2bf(hi) << 16); }
; __device__ __forceinline__ void transpose_item(const float* W, int N, bf16* WT, int ldo, int koff, int orow0, int k0, int n0, LAS float* scr, int lane, const float* gk) {
; #pragma unroll 8
;     for (int i = 0; i < 32; ++i) { const int kk = 2 * i + (lane >> 5); scr[kk * 33 + (lane & 31)] = __builtin_nontemporal_load(&W[(size_t)(k0 + kk) * N + n0 + (lane & 31)]); }
;     LDS_WAIT(); asm volatile("" ::: "memory");
;     const int c = lane & 7;
;     f32x4 g0 = {1.f, 1.f, 1.f, 1.f}, g1 = g0; if (gk) { g0 = *(const GAS f32x4*)(gk + k0 + 8 * c); g1 = *(const GAS f32x4*)(gk + k0 + 8 * c + 4); }
; #pragma unroll
;     for (int j = 0; j < 4; ++j) { const int n = (lane >> 3) + 8 * j; const LAS float* s = scr + (8 * c) * 33 + n;
;         v4u o; o.x = pk2(s[0 * 33] * g0.x, s[1 * 33] * g0.y); o.y = pk2(s[2 * 33] * g0.z, s[3 * 33] * g0.w); o.z = pk2(s[4 * 33] * g1.x, s[5 * 33] * g1.y); o.w = pk2(s[6 * 33] * g1.z, s[7 * 33] * g1.w);
;         __builtin_nontemporal_store(o, (GAS v4u*)(WT + (size_t)(orow0 + n) * ldo + koff + k0 + 8 * c)); }
;     LDS_WAIT(); asm volatile("" ::: "memory");
; }
.LBB0_13:
	v_mov_b32_e32 v2, v96
	v_mov_b32_e32 v16, v97
	v_mov_b32_e32 v3, v98
	v_mov_b32_e32 v17, v99
	v_mov_b32_e32 v6, v100
	v_mov_b32_e32 v4, v101
	v_mov_b32_e32 v7, v102
	v_mov_b32_e32 v5, v103

; #define GAS __attribute__((address_space(1)))
; #define LDS_WAIT() asm volatile("s_waitcnt lgkmcnt(0)" ::: "memory")
; __device__ __forceinline__ void transpose_item(const float* W, int N, bf16* WT, int ldo, int koff, int orow0, int k0, int n0, LAS float* scr, int lane, const float* gk) {
;     ...
;     for (int i = 0; i < 32; ++i) { const int kk = 2 * i + (lane >> 5); scr[kk * 33 + (lane & 31)] = __builtin_nontemporal_load(&W[(size_t)(k0 + kk) * N + n0 + (lane & 31)]); }
;     LDS_WAIT(); asm volatile("" ::: "memory");
;     const int c = lane & 7;
;     f32x4 g0 = {1.f, 1.f, 1.f, 1.f}, g1 = g0; if (gk) { g0 = *(const GAS f32x4*)(gk + k0 + 8 * c); g1 = *(const GAS f32x4*)(gk + k0 + 8 * c + 4); }
.LBB0_48:
	s_cmp_lg_u64 s[40:41], 0
	s_cbranch_scc0 .Ltr_nogk
	s_lshl_b32 s46, s43, 8
	s_add_u32 s40, s40, s46
	s_addc_u32 s41, s41, 0
	global_load_dwordx4 v[96:99], v24, s[40:41] offset:16
	global_load_dwordx4 v[100:103], v24, s[40:41]
.Ltr_nogk:
	v_mul_lo_u32 v92, v4, s58
	s_lshl_b32 s46, s58, 3
	s_mov_b32 s47, 0
	v_mov_b32_e32 v93, 0
	v_lshlrev_b32_e32 v92, 2, v92
	v_mov_b32_e32 v94, v23
	v_lshl_add_u64 v[92:93], v[2:3], 0, v[92:93]
	global_load_dword v60, v[92:93], off nt
	v_lshl_add_u64 v[92:93], v[92:93], 0, s[46:47]
	global_load_dword v61, v[92:93], off nt
	v_lshl_add_u64 v[92:93], v[92:93], 0, s[46:47]
	global_load_dword v62, v[92:93], off nt
	v_lshl_add_u64 v[92:93], v[92:93], 0, s[46:47]
	global_load_dword v63, v[92:93], off nt
	v_lshl_add_u64 v[92:93], v[92:93], 0, s[46:47]
	global_load_dword v64, v[92:93], off nt
	v_lshl_add_u64 v[92:93], v[92:93], 0, s[46:47]
	global_load_dword v65, v[92:93], off nt
	v_lshl_add_u64 v[92:93], v[92:93], 0, s[46:47]
	global_load_dword v66, v[92:93], off nt
	v_lshl_add_u64 v[92:93], v[92:93], 0, s[46:47]
	global_load_dword v67, v[92:93], off nt
	v_lshl_add_u64 v[92:93], v[92:93], 0, s[46:47]
	global_load_dword v68, v[92:93], off nt
	v_lshl_add_u64 v[92:93], v[92:93], 0, s[46:47]
	global_load_dword v69, v[92:93], off nt
	v_lshl_add_u64 v[92:93], v[92:93], 0, s[46:47]
	global_load_dword v70, v[92:93], off nt
	v_lshl_add_u64 v[92:93], v[92:93], 0, s[46:47]
	global_load_dword v71, v[92:93], off nt
	v_lshl_add_u64 v[92:93], v[92:93], 0, s[46:47]
	global_load_dword v72, v[92:93], off nt
	v_lshl_add_u64 v[92:93], v[92:93], 0, s[46:47]
	global_load_dword v73, v[92:93], off nt
	v_lshl_add_u64 v[92:93], v[92:93], 0, s[46:47]
	global_load_dword v74, v[92:93], off nt
	v_lshl_add_u64 v[92:93], v[92:93], 0, s[46:47]
	global_load_dword v75, v[92:93], off nt
	v_lshl_add_u64 v[92:93], v[92:93], 0, s[46:47]
	global_load_dword v76, v[92:93], off nt
	v_lshl_add_u64 v[92:93], v[92:93], 0, s[46:47]
	global_load_dword v77, v[92:93], off nt
	v_lshl_add_u64 v[92:93], v[92:93], 0, s[46:47]
	global_load_dword v78, v[92:93], off nt
	v_lshl_add_u64 v[92:93], v[92:93], 0, s[46:47]
	global_load_dword v79, v[92:93], off nt
	v_lshl_add_u64 v[92:93], v[92:93], 0, s[46:47]
	global_load_dword v80, v[92:93], off nt
	v_lshl_add_u64 v[92:93], v[92:93], 0, s[46:47]
	global_load_dword v81, v[92:93], off nt
	v_lshl_add_u64 v[92:93], v[92:93], 0, s[46:47]
	global_load_dword v82, v[92:93], off nt
	v_lshl_add_u64 v[92:93], v[92:93], 0, s[46:47]
	global_load_dword v83, v[92:93], off nt
	v_lshl_add_u64 v[92:93], v[92:93], 0, s[46:47]
	global_load_dword v84, v[92:93], off nt
	v_lshl_add_u64 v[92:93], v[92:93], 0, s[46:47]
	global_load_dword v85, v[92:93], off nt
	v_lshl_add_u64 v[92:93], v[92:93], 0, s[46:47]
	global_load_dword v86, v[92:93], off nt
	v_lshl_add_u64 v[92:93], v[92:93], 0, s[46:47]
	global_load_dword v87, v[92:93], off nt
	v_lshl_add_u64 v[92:93], v[92:93], 0, s[46:47]
	global_load_dword v88, v[92:93], off nt
	v_lshl_add_u64 v[92:93], v[92:93], 0, s[46:47]
	global_load_dword v89, v[92:93], off nt
	v_lshl_add_u64 v[92:93], v[92:93], 0, s[46:47]
	global_load_dword v90, v[92:93], off nt
	v_lshl_add_u64 v[92:93], v[92:93], 0, s[46:47]
	global_load_dword v91, v[92:93], off nt
	v_add_u32_e32 v95, 0x420, v94
	s_waitcnt vmcnt(30)
	ds_write2_b32 v94, v60, v61 offset1:66
	s_waitcnt vmcnt(28)
	ds_write2_b32 v94, v62, v63 offset0:132 offset1:198
	v_add_u32_e32 v94, 0x840, v94
	s_waitcnt vmcnt(26)
	ds_write2_b32 v95, v64, v65 offset1:66
	s_waitcnt vmcnt(24)
	ds_write2_b32 v95, v66, v67 offset0:132 offset1:198
	v_add_u32_e32 v95, 0x840, v95
	s_waitcnt vmcnt(22)
	ds_write2_b32 v94, v68, v69 offset1:66
	s_waitcnt vmcnt(20)
	ds_write2_b32 v94, v70, v71 offset0:132 offset1:198
	v_add_u32_e32 v94, 0x840, v94
	s_waitcnt vmcnt(18)
	ds_write2_b32 v95, v72, v73 offset1:66
	s_waitcnt vmcnt(16)
	ds_write2_b32 v95, v74, v75 offset0:132 offset1:198
	v_add_u32_e32 v95, 0x840, v95
	s_waitcnt vmcnt(14)
	ds_write2_b32 v94, v76, v77 offset1:66
	s_waitcnt vmcnt(12)
	ds_write2_b32 v94, v78, v79 offset0:132 offset1:198
	v_add_u32_e32 v94, 0x840, v94
	s_waitcnt vmcnt(10)
	ds_write2_b32 v95, v80, v81 offset1:66
	s_waitcnt vmcnt(8)
	ds_write2_b32 v95, v82, v83 offset0:132 offset1:198
	v_add_u32_e32 v95, 0x840, v95
	s_waitcnt vmcnt(6)
	ds_write2_b32 v94, v84, v85 offset1:66
	s_waitcnt vmcnt(4)
	ds_write2_b32 v94, v86, v87 offset0:132 offset1:198
	s_waitcnt vmcnt(2)
	ds_write2_b32 v95, v88, v89 offset1:66
	s_waitcnt vmcnt(0)
	ds_write2_b32 v95, v90, v91 offset0:132 offset1:198
	s_waitcnt lgkmcnt(0)
	s_lshl_b32 s42, s43, 6
	s_ashr_i32 s43, s42, 31
	s_cmp_lg_u64 s[40:41], 0
	s_cbranch_scc1 .LBB0_13
	v_mov_b32_e32 v2, 1.0
	v_mov_b32_e32 v16, 1.0
	v_mov_b32_e32 v3, v2
	v_mov_b32_e32 v17, v2
	v_mov_b32_e32 v6, v2
	v_mov_b32_e32 v4, v2
	v_mov_b32_e32 v7, v2
	v_mov_b32_e32 v5, v2
	s_branch .LBB0_14
